# v47 + 12 of the 18 top-of-chunk loads spread through conv group 1
# speedup vs baseline: 1.0068x; 1.0068x over previous
.LBB0_336:
	v_readlane_b32 s98, v254, 52
	v_readlane_b32 s99, v254, 53
	v_readfirstlane_b32 s100, v158
	s_nop 3
	v_subrev_u32_e32 v151, s98, v176
	s_add_i32 s100, s100, s13
	s_lshl_b32 s100, s100, 13
	s_add_u32 s98, s98, s100
	s_addc_u32 s99, s99, 0
	s_add_u32 s98, s98, 0x1c000
	s_addc_u32 s99, s99, 0
	global_load_dword v108, v151, s[98:99]
	s_add_u32 s98, s98, 0x2000
	s_addc_u32 s99, s99, 0
	global_load_dword v107, v151, s[98:99]
	s_add_u32 s98, s98, 0x2000
	s_addc_u32 s99, s99, 0
	global_load_dword v106, v151, s[98:99]
	s_add_u32 s98, s98, 0x2000
	s_addc_u32 s99, s99, 0
	global_load_dword v105, v151, s[98:99]
	s_add_u32 s98, s98, 0x2000
	s_addc_u32 s99, s99, 0
	global_load_dword v104, v151, s[98:99]
	s_add_u32 s98, s98, 0x2000
	s_addc_u32 s99, s99, 0
	global_load_dword v103, v151, s[98:99]
	s_andn2_b64 vcc, exec, s[92:93]
	s_cbranch_vccnz .LBB0_340
	s_cmp_eq_u32 s13, 0
	s_cbranch_scc1 .Ldtw_first
	s_waitcnt vmcnt(27)
	s_branch .Ldtw_join
.Ldtw_first:
	s_waitcnt vmcnt(6)

.LBB0_343:
.LBB0_344:
	s_andn2_saveexec_b64 s[94:95], s[94:95]
	s_cbranch_execz .LBB0_346
	s_waitcnt vmcnt(24)
	v_lshlrev_b32_e32 v72, 16, v250
	v_and_b32_e32 v73, 0xffff0000, v250
	v_lshlrev_b32_e32 v74, 16, v251
	v_and_b32_e32 v75, 0xffff0000, v251
	v_lshlrev_b32_e32 v76, 16, v252
	v_and_b32_e32 v77, 0xffff0000, v252
.LBB0_346:
	s_or_b64 exec, exec, s[94:95]
	s_waitcnt vmcnt(16)
	v_lshlrev_b32_e32 v78, 16, v249
	v_and_b32_e32 v79, 0xffff0000, v249
	v_pk_fma_f32 v[80:81], v[172:173], v[78:79], v[174:175]
	v_lshlrev_b32_e32 v88, 16, v247
	v_pk_fma_f32 v[80:81], v[170:171], v[76:77], v[80:81]
	v_and_b32_e32 v89, 0xffff0000, v247
	v_pk_fma_f32 v[80:81], v[168:169], v[74:75], v[80:81]
	v_lshlrev_b32_e32 v90, 16, v246
	v_pk_fma_f32 v[72:73], v[166:167], v[72:73], v[80:81]
	v_and_b32_e32 v91, 0xffff0000, v246
	v_pk_mul_f32 v[80:81], v[72:73], s[96:97] op_sel_hi:[1,0]
	v_lshlrev_b32_e32 v92, 16, v245
	s_add_u32 s98, s98, 0x2000
	s_addc_u32 s99, s99, 0
	global_load_dword v102, v151, s[98:99]
	v_exp_f32_e32 v80, v80
	v_exp_f32_e32 v81, v81
	v_and_b32_e32 v93, 0xffff0000, v245
	v_pk_add_f32 v[80:81], v[80:81], 1.0 op_sel_hi:[1,0]
	s_nop 0
	v_rcp_f32_e32 v80, v80
	v_rcp_f32_e32 v81, v81
	s_nop 0
	v_pk_mul_f32 v[72:73], v[72:73], v[80:81]
	v_lshlrev_b32_e32 v80, 16, v248
	v_and_b32_e32 v81, 0xffff0000, v248
	v_pk_fma_f32 v[82:83], v[172:173], v[80:81], v[174:175]
	s_add_u32 s98, s98, 0x2000
	s_addc_u32 s99, s99, 0
	global_load_dword v101, v151, s[98:99]
	s_nop 0
	v_pk_fma_f32 v[82:83], v[170:171], v[78:79], v[82:83]
	s_nop 0
	v_pk_fma_f32 v[82:83], v[168:169], v[76:77], v[82:83]
	s_nop 0
	v_pk_fma_f32 v[74:75], v[166:167], v[74:75], v[82:83]
	s_nop 0
	v_pk_mul_f32 v[82:83], v[74:75], s[96:97] op_sel_hi:[1,0]
	s_nop 0
	v_exp_f32_e32 v82, v82
	v_exp_f32_e32 v83, v83
	s_nop 0
	s_add_u32 s98, s98, 0x2000
	s_addc_u32 s99, s99, 0
	global_load_dword v100, v151, s[98:99]
	v_pk_add_f32 v[82:83], v[82:83], 1.0 op_sel_hi:[1,0]
	s_nop 0
	v_rcp_f32_e32 v82, v82
	v_rcp_f32_e32 v83, v83
	s_nop 0
	v_pk_mul_f32 v[74:75], v[74:75], v[82:83]
	v_pk_fma_f32 v[82:83], v[172:173], v[88:89], v[174:175]
	s_nop 0
	v_pk_fma_f32 v[82:83], v[170:171], v[80:81], v[82:83]
	s_nop 0
	v_pk_fma_f32 v[82:83], v[168:169], v[78:79], v[82:83]
	s_nop 0
	s_add_u32 s98, s98, 0x2000
	s_addc_u32 s99, s99, 0
	global_load_dword v99, v151, s[98:99]
	v_pk_fma_f32 v[76:77], v[166:167], v[76:77], v[82:83]
	s_nop 0
	v_pk_mul_f32 v[82:83], v[76:77], s[96:97] op_sel_hi:[1,0]
	s_nop 0
	v_exp_f32_e32 v82, v82
	v_exp_f32_e32 v83, v83
	s_nop 0
	v_pk_add_f32 v[82:83], v[82:83], 1.0 op_sel_hi:[1,0]
	s_nop 0
	v_rcp_f32_e32 v82, v82
	v_rcp_f32_e32 v83, v83
	s_nop 0
	s_add_u32 s98, s98, 0x2000
	s_addc_u32 s99, s99, 0
	global_load_dword v98, v151, s[98:99]
	v_pk_mul_f32 v[76:77], v[76:77], v[82:83]
	v_pk_fma_f32 v[82:83], v[172:173], v[90:91], v[174:175]
	s_nop 0
	v_pk_fma_f32 v[82:83], v[170:171], v[88:89], v[82:83]
	s_nop 0
	v_pk_fma_f32 v[82:83], v[168:169], v[80:81], v[82:83]
	s_nop 0
	v_pk_fma_f32 v[78:79], v[166:167], v[78:79], v[82:83]
	s_nop 0
	v_pk_mul_f32 v[82:83], v[78:79], s[96:97] op_sel_hi:[1,0]
	s_nop 0
	v_exp_f32_e32 v82, v82
	s_add_u32 s98, s98, 0x2000
	s_addc_u32 s99, s99, 0
	global_load_dword v97, v151, s[98:99]
	v_exp_f32_e32 v83, v83
	s_nop 0
	v_pk_add_f32 v[82:83], v[82:83], 1.0 op_sel_hi:[1,0]
	s_nop 0
	v_rcp_f32_e32 v82, v82
	v_rcp_f32_e32 v83, v83
	s_nop 0
	v_pk_mul_f32 v[84:85], v[78:79], v[82:83]
	v_pk_fma_f32 v[78:79], v[172:173], v[92:93], v[174:175]
	v_lshlrev_b32_e32 v82, 16, v244
	v_pk_fma_f32 v[78:79], v[170:171], v[90:91], v[78:79]
	v_and_b32_e32 v83, 0xffff0000, v244
	s_add_u32 s98, s98, 0x2000
	s_addc_u32 s99, s99, 0
	global_load_dword v96, v151, s[98:99]
	v_pk_fma_f32 v[78:79], v[168:169], v[88:89], v[78:79]
	s_nop 0
	v_pk_fma_f32 v[78:79], v[166:167], v[80:81], v[78:79]
	s_nop 0
	v_pk_mul_f32 v[80:81], v[78:79], s[96:97] op_sel_hi:[1,0]
	s_nop 0
	v_exp_f32_e32 v80, v80
	v_exp_f32_e32 v81, v81
	s_nop 0
	v_pk_add_f32 v[80:81], v[80:81], 1.0 op_sel_hi:[1,0]
	s_nop 0
	v_rcp_f32_e32 v80, v80
	s_add_u32 s98, s98, 0x2000
	s_addc_u32 s99, s99, 0
	global_load_dword v95, v151, s[98:99]
	v_rcp_f32_e32 v81, v81
	s_nop 0
	v_pk_mul_f32 v[86:87], v[78:79], v[80:81]
	v_pk_fma_f32 v[78:79], v[172:173], v[82:83], v[174:175]
	s_nop 0
	v_pk_fma_f32 v[78:79], v[170:171], v[92:93], v[78:79]
	s_nop 0
	v_pk_fma_f32 v[78:79], v[168:169], v[90:91], v[78:79]
	s_nop 0
	v_pk_fma_f32 v[78:79], v[166:167], v[88:89], v[78:79]
	s_nop 0
	v_pk_mul_f32 v[80:81], v[78:79], s[96:97] op_sel_hi:[1,0]
	s_add_u32 s98, s98, 0x2000
	s_addc_u32 s99, s99, 0
	global_load_dword v94, v151, s[98:99]
	s_nop 0
	v_exp_f32_e32 v80, v80
	v_exp_f32_e32 v81, v81
	s_nop 0
	v_pk_add_f32 v[80:81], v[80:81], 1.0 op_sel_hi:[1,0]
	s_nop 0
	v_rcp_f32_e32 v80, v80
	v_rcp_f32_e32 v81, v81
	s_nop 0
	v_pk_mul_f32 v[88:89], v[78:79], v[80:81]
	v_lshlrev_b32_e32 v80, 16, v243
	v_and_b32_e32 v81, 0xffff0000, v243
	s_add_u32 s98, s98, 0x2000
	s_addc_u32 s99, s99, 0
	global_load_dword v3, v151, s[98:99]
	v_pk_fma_f32 v[78:79], v[172:173], v[80:81], v[174:175]
	s_nop 0
	v_pk_fma_f32 v[78:79], v[170:171], v[82:83], v[78:79]
	s_nop 0
	v_pk_fma_f32 v[78:79], v[168:169], v[92:93], v[78:79]
	s_nop 0
	v_pk_fma_f32 v[78:79], v[166:167], v[90:91], v[78:79]
	s_nop 0
	v_pk_mul_f32 v[90:91], v[78:79], s[96:97] op_sel_hi:[1,0]
	s_nop 0
	v_exp_f32_e32 v90, v90
	v_exp_f32_e32 v91, v91
	s_add_u32 s98, s98, 0x2000
	s_addc_u32 s99, s99, 0
	global_load_dword v69, v151, s[98:99]
	s_nop 0
	v_pk_add_f32 v[90:91], v[90:91], 1.0 op_sel_hi:[1,0]
	s_nop 0
	v_rcp_f32_e32 v90, v90
	v_rcp_f32_e32 v91, v91
	s_nop 0
	v_pk_mul_f32 v[90:91], v[78:79], v[90:91]
	v_lshlrev_b32_e32 v78, 16, v242
	v_and_b32_e32 v79, 0xffff0000, v242
	v_pk_fma_f32 v[110:111], v[172:173], v[78:79], v[174:175]
	s_nop 0
	v_pk_fma_f32 v[110:111], v[170:171], v[80:81], v[110:111]
	s_add_u32 s98, s98, 0x2000
	s_addc_u32 s99, s99, 0
	global_load_dword v71, v151, s[98:99]
	s_nop 0
	v_pk_fma_f32 v[110:111], v[168:169], v[82:83], v[110:111]
	s_nop 0
	v_pk_fma_f32 v[92:93], v[166:167], v[92:93], v[110:111]
	s_nop 0
	v_pk_mul_f32 v[110:111], v[92:93], s[96:97] op_sel_hi:[1,0]
	s_nop 0
	v_exp_f32_e32 v110, v110
	v_exp_f32_e32 v111, v111
	s_nop 0
	v_pk_add_f32 v[110:111], v[110:111], 1.0 op_sel_hi:[1,0]
	s_nop 0
	v_rcp_f32_e32 v110, v110
	v_rcp_f32_e32 v111, v111
	s_nop 0
	v_pk_mul_f32 v[92:93], v[92:93], v[110:111]
	s_and_saveexec_b64 s[16:17], s[4:5]
	s_xor_b64 s[94:95], exec, s[16:17]
	s_cbranch_execz .LBB0_354
	s_and_saveexec_b64 s[16:17], s[8:9]
	s_xor_b64 vcc, exec, s[16:17]
	s_cbranch_execz .LBB0_351
	v_cvt_pk_bf16_f32 v72, v72, v73
	ds_write_b32 v213, v72
	v_cvt_pk_bf16_f32 v72, v74, v75
	ds_write_b32 v214, v72
	v_cvt_pk_bf16_f32 v72, v76, v77
	ds_write_b32 v215, v72
	v_cvt_pk_bf16_f32 v72, v84, v85
	ds_write_b32 v212, v72 offset:48
	v_cvt_pk_bf16_f32 v72, v86, v87
	ds_write_b32 v212, v72 offset:320
	v_cvt_pk_bf16_f32 v72, v88, v89
	ds_write_b32 v212, v72 offset:592
	v_cvt_pk_bf16_f32 v72, v90, v91
	ds_write_b32 v212, v72 offset:864
	v_cvt_pk_bf16_f32 v72, v92, v93
	ds_write_b32 v212, v72 offset:1136
